# within-XCD start stagger (odd within-XCD workgroups start 1.5 us late) on the P2, P5 and P9 GEMM phases so tile-epilogue store bursts of one XCD do not coincide
# baseline (speedup 1.0000x reference)
.LBB0_204:
	s_or_b64 exec, exec, s[2:3]
	v_readlane_b32 s2, v254, 51
	v_readlane_b32 s3, v254, 52
	s_xor_b64 s[2:3], s[2:3], -1
	v_writelane_b32 v252, s2, 12
	v_readlane_b32 s10, v254, 15
	s_mov_b32 s6, 27
	v_writelane_b32 v252, s3, 13
	s_mov_b32 s4, 27
	s_mov_b32 s2, 27
	v_mov_b32_e32 v10, v196
	v_readlane_b32 s11, v254, 16
	s_waitcnt lgkmcnt(0)
	s_barrier
	v_readlane_b32 s98, v254, 56
	s_bfe_u32 s98, s98, 0x10003
	s_cmp_eq_u32 s98, 0
	s_cbranch_scc1 .Lstag_done_204
	s_memrealtime s[100:101]
	s_waitcnt lgkmcnt(0)
	s_add_u32 s100, s100, 150
.Lstag_loop_204:
	s_sleep 2
	s_memrealtime s[98:99]
	s_waitcnt lgkmcnt(0)
	s_sub_u32 s99, s100, s98
	s_cmp_gt_i32 s99, 0
	s_cbranch_scc1 .Lstag_loop_204
.Lstag_done_204:
	s_and_b64 vcc, exec, s[10:11]
	v_readfirstlane_b32 s8, v10
	s_cbranch_vccz .LBB0_220
	s_ashr_i32 s7, s6, 31
	s_lshl_b64 s[6:7], s[6:7], 3
	s_add_u32 s6, s0, s6
	s_addc_u32 s7, s1, s7
	s_load_dwordx2 s[6:7], s[6:7], 0x0
	v_lshlrev_b32_e32 v0, 4, v10
	v_add_u32_e32 v2, 0x2000, v0
	v_ashrrev_i32_e32 v3, 31, v2
	v_lshrrev_b32_e32 v3, 22, v3
	v_add_u32_e32 v3, v2, v3
	s_waitcnt lgkmcnt(0)
	s_add_u32 s24, s6, 0x3a00000
	v_ashrrev_i32_e32 v11, 10, v3
	s_addc_u32 s25, s7, 0
	s_ashr_i32 s5, s4, 31
	v_mul_i32_i24_e32 v3, 0x400, v11
	s_lshl_b64 s[4:5], s[4:5], 3
	v_sub_u32_e32 v2, v2, v3
	s_add_u32 s4, s0, s4
	v_lshrrev_b32_e32 v3, 4, v2
	s_addc_u32 s5, s1, s5
	v_bitop3_b32 v2, v3, v2, 32 bitop3:0x6c
	s_load_dwordx2 s[4:5], s[4:5], 0x0
	v_ashrrev_i32_e32 v3, 31, v2
	v_lshrrev_b32_e32 v3, 26, v3
	v_add_u32_e32 v3, v2, v3
	v_lshlrev_b32_e32 v4, 3, v11
	v_ashrrev_i32_e32 v12, 6, v3
	v_and_b32_e32 v4, -16, v4
	v_add_u32_e32 v4, v12, v4
	s_waitcnt lgkmcnt(0)
	s_add_u32 s26, s4, 0x100000
	v_and_b32_e32 v5, 3, v12
	s_mov_b32 s4, 0x1fffe0
	v_lshrrev_b32_e32 v6, 2, v4
	v_lshlrev_b32_e32 v7, 1, v4
	v_and_b32_e32 v3, 0xc0, v3
	v_and_or_b32 v5, v4, s4, v5
	v_and_b32_e32 v6, 4, v6
	v_and_b32_e32 v7, 24, v7
	v_sub_u32_e32 v2, v2, v3
	v_or3_b32 v5, v5, v6, v7
	v_lshlrev_b32_e32 v6, 5, v11
	v_ashrrev_i16_sdwa v2, v199, sext(v2) dst_sel:DWORD dst_unused:UNUSED_PAD src0_sel:DWORD src1_sel:BYTE_0
	v_and_b32_e32 v6, 32, v6
	v_bfe_i32 v13, v2, 0, 16
	v_add_lshl_u32 v2, v6, v13, 1
	v_lshl_add_u32 v130, v5, 11, v2
	v_lshl_add_u32 v132, v4, 11, v2
	v_bfe_i32 v2, v10, 27, 1
	v_lshrrev_b32_e32 v2, 22, v2
	v_add_u32_e32 v2, v0, v2
	v_and_b32_e32 v2, 0xfffffc00, v2
	v_sub_u32_e32 v0, v0, v2
	v_lshrrev_b32_e32 v2, 4, v0
	v_ashrrev_i32_e32 v3, 31, v10
	v_bitop3_b32 v0, v2, v0, 32 bitop3:0x6c
	v_lshrrev_b32_e32 v3, 26, v3
	v_ashrrev_i32_e32 v2, 31, v0
	v_add_u32_e32 v3, v10, v3
	s_addc_u32 s27, s5, 0
	s_ashr_i32 s3, s2, 31
	v_lshrrev_b32_e32 v2, 26, v2
	v_ashrrev_i32_e32 v15, 6, v3
	s_lshl_b64 s[2:3], s[2:3], 3
	v_add_u32_e32 v2, v0, v2
	v_lshlrev_b32_e32 v3, 3, v15
	s_add_u32 s2, s0, s2
	v_ashrrev_i32_e32 v14, 6, v2
	v_and_b32_e32 v3, -16, v3
	s_addc_u32 s3, s1, s3
	s_ashr_i32 s7, s8, 6
	v_add_u32_e32 v3, v14, v3
	v_and_b32_e32 v4, 3, v14
	s_ashr_i32 s6, s8, 8
	s_lshl_b32 s28, s7, 10
	v_and_or_b32 v4, v3, s4, v4
	v_lshrrev_b32_e32 v5, 2, v3
	v_lshlrev_b32_e32 v6, 1, v3
	v_and_b32_e32 v2, 0xc0, v2
	v_readlane_b32 s4, v254, 37
	v_and_b32_e32 v5, 4, v5
	v_and_b32_e32 v6, 24, v6
	v_sub_u32_e32 v0, v0, v2
	v_readlane_b32 s5, v254, 38
	s_add_u32 s18, s24, s4
	v_or3_b32 v4, v4, v5, v6
	v_lshlrev_b32_e32 v5, 5, v15
	v_ashrrev_i16_sdwa v0, v199, sext(v0) dst_sel:DWORD dst_unused:UNUSED_PAD src0_sel:DWORD src1_sel:BYTE_0
	s_addc_u32 s19, s25, s5
	v_readlane_b32 s4, v254, 33
	v_and_b32_e32 v5, 32, v5
	v_bfe_i32 v16, v0, 0, 16
	v_readlane_b32 s5, v254, 34
	s_add_u32 s20, s26, s4
	v_add_lshl_u32 v2, v5, v16, 1
	s_addc_u32 s21, s27, s5
	s_add_i32 s29, s28, 0
	v_lshl_add_u32 v0, v4, 11, v2
	s_add_i32 m0, s29, 0x10000
	v_lshl_add_u32 v134, v3, 11, v2
	global_load_lds_dwordx4 v0, s[20:21]
	s_add_i32 m0, s29, 0x12000
	s_add_u32 s4, s20, 0x40000
	global_load_lds_dwordx4 v130, s[20:21]
	s_addc_u32 s5, s21, 0
	s_add_i32 m0, s29, 0x14000
	s_add_i32 s30, s29, 0x2000
	global_load_lds_dwordx4 v0, s[4:5]
	s_add_i32 m0, s29, 0x16000
	v_mov_b32_e32 v131, v1
	global_load_lds_dwordx4 v130, s[4:5]
	s_mov_b32 m0, s29
	s_add_u32 s4, s18, 0x40000
	global_load_lds_dwordx4 v134, s[18:19]
	s_mov_b32 m0, s30
	s_addc_u32 s5, s19, 0
	s_add_i32 s31, s29, 0x4000
	global_load_lds_dwordx4 v132, s[18:19]
	s_mov_b32 m0, s31
	s_add_i32 s34, s29, 0x6000
	global_load_lds_dwordx4 v134, s[4:5]
	s_mov_b32 m0, s34
	v_mov_b32_e32 v135, v1
	global_load_lds_dwordx4 v132, s[4:5]
	s_load_dwordx2 s[4:5], s[2:3], 0x0
	v_mov_b32_e32 v133, v1
	s_cmp_eq_u32 s6, 1
	v_lshl_add_u64 v[8:9], s[20:21], 0, v[0:1]
	v_lshl_add_u64 v[6:7], s[20:21], 0, v[130:131]
	v_lshl_add_u64 v[2:3], s[18:19], 0, v[134:135]
	s_cselect_b64 s[2:3], -1, 0
	s_cmp_lg_u32 s6, 1
	v_lshl_add_u64 v[4:5], s[18:19], 0, v[132:133]
	s_cbranch_scc1 .LBB0_207
	s_barrier

.LBB0_672:
	s_or_b64 exec, exec, s[2:3]
	v_readlane_b32 s2, v254, 51
	v_readlane_b32 s3, v254, 52
	s_and_b64 s[2:3], s[2:3], exec
	v_readlane_b32 s10, v252, 1
	s_cselect_b32 s34, 0x80, s75
	v_readlane_b32 s11, v252, 2
	s_mul_i32 s46, s34, 12
	s_mov_b32 s6, 27
	s_mov_b32 s4, 27
	s_mov_b32 s2, 27
	v_mov_b32_e32 v11, v196
	v_cndmask_b32_e64 v0, 0, 1, s[10:11]
	s_waitcnt lgkmcnt(0)
	s_barrier
	v_readlane_b32 s98, v254, 56
	s_bfe_u32 s98, s98, 0x10003
	s_cmp_eq_u32 s98, 0
	s_cbranch_scc1 .Lstag_done_672
	s_memrealtime s[100:101]
	s_waitcnt lgkmcnt(0)
	s_add_u32 s100, s100, 150

.Lstag_done_672:
	s_cmp_lt_i32 s73, s46
	v_cmp_ne_u32_e64 s[38:39], 1, v0
	v_readfirstlane_b32 s8, v11
	s_cbranch_scc0 .LBB0_691
	s_ashr_i32 s7, s6, 31
	s_lshr_b32 s26, s46, 3
	s_lshl_b64 s[6:7], s[6:7], 3
	s_add_u32 s6, s0, s6
	s_addc_u32 s7, s1, s7
	s_ashr_i32 s5, s4, 31
	s_lshl_b64 s[4:5], s[4:5], 3
	s_add_u32 s4, s0, s4
	s_addc_u32 s5, s1, s5
	s_ashr_i32 s3, s2, 31
	s_lshl_b64 s[2:3], s[2:3], 3
	s_add_u32 s10, s0, s2
	v_readlane_b32 s9, v254, 32
	s_addc_u32 s11, s1, s3
	s_load_dwordx2 s[6:7], s[6:7], 0x0
	s_nop 0
	s_load_dwordx2 s[2:3], s[4:5], 0x0
	s_nop 0
	s_load_dwordx2 s[4:5], s[10:11], 0x0
	s_or_b32 s9, s26, s9
	v_readlane_b32 s10, v254, 31
	s_mul_i32 s9, s9, s10
	v_readlane_b32 s10, v254, 30
	s_add_i32 s9, s9, s10
	s_mul_hi_i32 s10, s9, 0x2aaaaaab
	s_lshr_b32 s11, s10, 31
	s_ashr_i32 s10, s10, 4
	s_add_i32 s10, s10, s11
	s_lshl_b32 s12, s10, 3
	s_sub_i32 s11, s34, s12
	s_min_i32 s13, s11, 8
	s_sext_i32_i8 s11, s13
	v_cvt_f32_i32_e32 v0, s11
	s_mulk_i32 s10, 0x60
	s_sub_i32 s14, s9, s10
	v_cvt_f32_i32_e32 v2, s14
	v_rcp_iflag_f32_e32 v3, v0
	s_xor_b32 s9, s14, s11
	s_ashr_i32 s9, s9, 30
	s_or_b32 s9, s9, 1
	v_mul_f32_e32 v3, v2, v3
	v_trunc_f32_e32 v3, v3
	v_fma_f32 v2, -v3, v0, v2
	v_cvt_i32_f32_e32 v3, v3
	v_cmp_ge_f32_e64 s[10:11], |v2|, |v0|
	s_and_b64 s[10:11], s[10:11], exec
	s_cselect_b32 s9, s9, 0
	v_readfirstlane_b32 s10, v3
	s_add_i32 s9, s10, s9
	s_mul_i32 s10, s9, s13
	s_sub_i32 s10, s14, s10
	s_sext_i32_i8 s10, s10
	s_and_b64 vcc, exec, s[38:39]
	s_add_i32 s18, s12, s10
	s_cbranch_vccnz .LBB0_675
	s_ashr_i32 s10, s18, 5
	s_mul_i32 s10, s10, 33
	s_and_b32 s11, s18, 31
	s_add_i32 s10, s11, s10
	s_add_i32 s18, s10, 1

.LBB0_1013:
	s_or_b64 exec, exec, s[2:3]
	s_mul_i32 s46, s34, 22
	s_cmp_lt_i32 s73, s46
	s_mov_b32 s4, 27
	s_waitcnt lgkmcnt(0)
	s_barrier
	s_cselect_b64 s[2:3], -1, 0
	v_readlane_b32 s98, v254, 56
	s_bfe_u32 s98, s98, 0x10003
	s_cmp_eq_u32 s98, 0
	s_cbranch_scc1 .Lstag_done_1013
	s_memrealtime s[100:101]
	s_waitcnt lgkmcnt(0)
	s_add_u32 s100, s100, 150

.Lstag_done_1013:
	s_ashr_i32 s5, s4, 31
	s_lshr_b32 s36, s46, 3
	s_lshl_b64 s[4:5], s[4:5], 3
	s_add_u32 s4, s0, s4
	s_addc_u32 s5, s1, s5
	s_load_dwordx2 s[8:9], s[4:5], 0x0
	s_mov_b32 s4, 27
	s_ashr_i32 s5, s4, 31
	s_lshl_b64 s[4:5], s[4:5], 3
	s_add_u32 s4, s0, s4
	s_addc_u32 s5, s1, s5
	s_load_dwordx2 s[10:11], s[4:5], 0x0
	s_mov_b32 s4, 27
	s_ashr_i32 s5, s4, 31
	s_lshl_b64 s[4:5], s[4:5], 3
	s_add_u32 s4, s0, s4
	s_addc_u32 s5, s1, s5
	s_mov_b32 s6, 27
	s_load_dwordx2 s[4:5], s[4:5], 0x0
	s_ashr_i32 s7, s6, 31
	s_lshl_b64 s[6:7], s[6:7], 3
	s_add_u32 s6, s0, s6
	s_addc_u32 s7, s1, s7
	s_load_dwordx2 s[6:7], s[6:7], 0x0
	v_mov_b32_e32 v11, v196
	s_and_b64 vcc, exec, s[2:3]
	v_readfirstlane_b32 s12, v11
	s_cbranch_vccz .LBB0_1017
	v_readlane_b32 s13, v254, 32
	s_add_i32 s13, s36, s13
	v_readlane_b32 s14, v254, 31
	s_mul_i32 s13, s13, s14
	v_readlane_b32 s14, v254, 30
	s_add_i32 s13, s13, s14
	s_mul_hi_i32 s14, s13, 0x2e8ba2e9
	s_lshr_b32 s15, s14, 31
	s_ashr_i32 s14, s14, 5
	s_add_i32 s14, s14, s15
	s_lshl_b32 s18, s14, 3
	s_sub_i32 s15, s34, s18
	s_min_i32 s19, s15, 8
	s_sext_i32_i16 s15, s19
	v_cvt_f32_i32_e32 v0, s15
	s_mulk_i32 s14, 0xb0
	s_sub_i32 s20, s13, s14
	v_cvt_f32_i32_e32 v2, s20
	v_rcp_iflag_f32_e32 v3, v0
	s_xor_b32 s13, s20, s15
	s_ashr_i32 s13, s13, 30
	s_or_b32 s13, s13, 1
	v_mul_f32_e32 v3, v2, v3
	v_trunc_f32_e32 v3, v3
	v_fma_f32 v2, -v3, v0, v2
	v_cvt_i32_f32_e32 v3, v3
	v_cmp_ge_f32_e64 s[14:15], |v2|, |v0|
	s_and_b64 s[14:15], s[14:15], exec
	s_cselect_b32 s13, s13, 0
	v_readfirstlane_b32 s14, v3
	s_add_i32 s13, s14, s13
	s_mul_i32 s14, s13, s19
	s_sub_i32 s14, s20, s14
	s_sext_i32_i16 s14, s14
	s_and_b64 vcc, exec, s[38:39]
	s_add_i32 s14, s18, s14
	s_cbranch_vccnz .LBB0_1016
	s_ashr_i32 s15, s14, 5
	s_mul_i32 s15, s15, 33
	s_and_b32 s14, s14, 31
	s_add_i32 s14, s14, s15
	s_add_i32 s14, s14, 1
